# st5 (cross-attn probabilities) on v_mfma_f32_16x16x32_bf16 with a re-derived softmax epilogue (cross-lane reduce via permlane16/32 swaps, LDS-staged P stores)
# speedup vs baseline: 1.0452x; 1.0073x over previous
.LBB0_741:
.Lst5_fin:
	s_waitcnt vmcnt(63) expcnt(7) lgkmcnt(15)
	s_barrier
	s_cbranch_vccnz .LBB0_768

.LBB0_744:
	v_lshl_add_u64 v[148:149], v[0:1], 0, s[66:67]
	v_mov_b32_e32 v0, 0
	v_lshl_add_u64 v[134:135], v[14:15], 0, s[66:67]
	v_lshl_add_u64 v[136:137], v[12:13], 0, s[66:67]
	v_lshl_add_u64 v[138:139], v[10:11], 0, s[66:67]
	v_lshl_add_u64 v[140:141], v[8:9], 0, s[66:67]
	v_lshl_add_u64 v[142:143], v[6:7], 0, s[66:67]
	v_lshl_add_u64 v[144:145], v[4:5], 0, s[66:67]
	v_lshl_add_u64 v[146:147], v[2:3], 0, s[66:67]
	s_mov_b32 s0, 0
	s_mov_b64 s[2:3], 0
	v_mov_b32_e32 v1, v0
	v_mov_b32_e32 v2, v0
	v_mov_b32_e32 v3, v0
	v_mov_b32_e32 v4, v0
	v_mov_b32_e32 v5, v0
	v_mov_b32_e32 v6, v0
	v_mov_b32_e32 v7, v0
	v_mov_b32_e32 v8, v0
	v_mov_b32_e32 v9, v0
	v_mov_b32_e32 v10, v0
	v_mov_b32_e32 v11, v0
	v_mov_b32_e32 v12, v0
	v_mov_b32_e32 v13, v0
	v_mov_b32_e32 v14, v0
	v_mov_b32_e32 v15, v0
	v_mov_b32_e32 v16, v0
	v_mov_b32_e32 v17, v0
	v_mov_b32_e32 v18, v0
	v_mov_b32_e32 v19, v0
	v_mov_b32_e32 v20, v0
	v_mov_b32_e32 v21, v0
	v_mov_b32_e32 v22, v0
	v_mov_b32_e32 v23, v0
	v_mov_b32_e32 v24, v0
	v_mov_b32_e32 v25, v0
	v_mov_b32_e32 v26, v0
	v_mov_b32_e32 v27, v0
	v_mov_b32_e32 v28, v0
	v_mov_b32_e32 v29, v0
	v_mov_b32_e32 v30, v0
	v_mov_b32_e32 v31, v0
	v_mov_b32_e32 v48, v0
	v_mov_b32_e32 v49, v0
	v_mov_b32_e32 v50, v0
	v_mov_b32_e32 v51, v0
	v_mov_b32_e32 v52, v0
	v_mov_b32_e32 v53, v0
	v_mov_b32_e32 v54, v0
	v_mov_b32_e32 v55, v0
	v_mov_b32_e32 v56, v0
	v_mov_b32_e32 v57, v0
	v_mov_b32_e32 v58, v0
	v_mov_b32_e32 v59, v0
	v_mov_b32_e32 v60, v0
	v_mov_b32_e32 v61, v0
	v_mov_b32_e32 v62, v0
	v_mov_b32_e32 v63, v0
	v_mov_b32_e32 v80, v0
	v_mov_b32_e32 v81, v0
	v_mov_b32_e32 v82, v0
	v_mov_b32_e32 v83, v0
	v_mov_b32_e32 v84, v0
	v_mov_b32_e32 v85, v0
	v_mov_b32_e32 v86, v0
	v_mov_b32_e32 v87, v0
	v_mov_b32_e32 v88, v0
	v_mov_b32_e32 v89, v0
	v_mov_b32_e32 v90, v0
	v_mov_b32_e32 v91, v0
	v_mov_b32_e32 v92, v0
	v_mov_b32_e32 v93, v0
	v_mov_b32_e32 v94, v0
	v_mov_b32_e32 v95, v0
	v_mov_b32_e32 v32, v0
	v_mov_b32_e32 v33, v0
	v_mov_b32_e32 v34, v0
	v_mov_b32_e32 v35, v0
	v_mov_b32_e32 v36, v0
	v_mov_b32_e32 v37, v0
	v_mov_b32_e32 v38, v0
	v_mov_b32_e32 v39, v0
	v_mov_b32_e32 v40, v0
	v_mov_b32_e32 v41, v0
	v_mov_b32_e32 v42, v0
	v_mov_b32_e32 v43, v0
	v_mov_b32_e32 v44, v0
	v_mov_b32_e32 v45, v0
	v_mov_b32_e32 v46, v0
	v_mov_b32_e32 v47, v0
	v_mov_b32_e32 v64, v0
	v_mov_b32_e32 v65, v0
	v_mov_b32_e32 v66, v0
	v_mov_b32_e32 v67, v0
	v_mov_b32_e32 v68, v0
	v_mov_b32_e32 v69, v0
	v_mov_b32_e32 v70, v0
	v_mov_b32_e32 v71, v0
	v_mov_b32_e32 v72, v0
	v_mov_b32_e32 v73, v0
	v_mov_b32_e32 v74, v0
	v_mov_b32_e32 v75, v0
	v_mov_b32_e32 v76, v0
	v_mov_b32_e32 v77, v0
	v_mov_b32_e32 v78, v0
	v_mov_b32_e32 v79, v0
	v_mov_b32_e32 v96, v0
	v_mov_b32_e32 v97, v0
	v_mov_b32_e32 v98, v0
	v_mov_b32_e32 v99, v0
	v_mov_b32_e32 v100, v0
	v_mov_b32_e32 v101, v0
	v_mov_b32_e32 v102, v0
	v_mov_b32_e32 v103, v0
	v_mov_b32_e32 v104, v0
	v_mov_b32_e32 v105, v0
	v_mov_b32_e32 v106, v0
	v_mov_b32_e32 v107, v0
	v_mov_b32_e32 v108, v0
	v_mov_b32_e32 v109, v0
	v_mov_b32_e32 v110, v0
	v_mov_b32_e32 v111, v0
	v_mov_b32_e32 v112, v0
	v_mov_b32_e32 v113, v0
	v_mov_b32_e32 v114, v0
	v_mov_b32_e32 v115, v0
	v_mov_b32_e32 v116, v0
	v_mov_b32_e32 v117, v0
	v_mov_b32_e32 v118, v0
	v_mov_b32_e32 v119, v0
	v_mov_b32_e32 v120, v0
	v_mov_b32_e32 v121, v0
	v_mov_b32_e32 v122, v0
	v_mov_b32_e32 v123, v0
	v_mov_b32_e32 v124, v0
	v_mov_b32_e32 v125, v0
	v_mov_b32_e32 v126, v0
	v_mov_b32_e32 v127, v0
	v_and_b32_e32 v238, 15, v184
	v_bfe_u32 v239, v184, 4, 2
	v_bfe_u32 v241, v184, 1, 3
	v_xor_b32_e32 v239, v239, v241
	v_lshlrev_b32_e32 v239, 4, v239
	v_lshl_add_u32 v239, v238, 7, v239
	v_lshrrev_b32_e32 v241, 8, v184
	v_lshl_add_u32 v236, v241, 14, v239
	v_bfe_u32 v241, v184, 6, 2
	v_lshl_add_u32 v237, v241, 13, v239
	v_add_u32_e32 v237, 0x8000, v237
.LBB0_745:
	s_add_i32 s1, s0, 0x10000
	s_and_b32 s16, s1, 0x10000
	s_and_b32 s0, s0, 0x10000
	s_add_i32 s0, s0, 16
	v_add_u32_e32 v240, s16, v161
	s_nop 0
	v_readfirstlane_b32 s16, v240
	s_waitcnt vmcnt(0)
	s_barrier
	v_add_u32_e32 v239, s0, v237
	ds_read_b128 v[202:205], v239
	ds_read_b128 v[206:209], v239 offset:2048
	ds_read_b128 v[210:213], v239 offset:4096
	ds_read_b128 v[214:217], v239 offset:6144
	v_add_u32_e32 v238, s0, v236
	ds_read_b128 v[218:221], v238
	ds_read_b128 v[180:183], v238 offset:2048
	ds_read_b128 v[222:225], v238 offset:4096
	ds_read_b128 v[226:229], v238 offset:6144
	v_lshl_add_u64 v[230:231], v[148:149], 0, s[2:3]
	s_mov_b32 m0, s16
	s_nop 0
	global_load_lds_dwordx4 v[230:231], off
	s_waitcnt lgkmcnt(3)
	v_mfma_f32_16x16x32_bf16 v[0:3], v[202:205], v[218:221], v[0:3]
	v_mfma_f32_16x16x32_bf16 v[32:35], v[206:209], v[218:221], v[32:35]
	v_lshl_add_u64 v[230:231], v[146:147], 0, s[2:3]
	s_add_i32 s17, s16, 0x2000
	s_mov_b32 m0, s17
	s_nop 0
	global_load_lds_dwordx4 v[230:231], off
	v_mfma_f32_16x16x32_bf16 v[64:67], v[210:213], v[218:221], v[64:67]
	v_mfma_f32_16x16x32_bf16 v[96:99], v[214:217], v[218:221], v[96:99]
	s_waitcnt lgkmcnt(2)
	v_mfma_f32_16x16x32_bf16 v[4:7], v[202:205], v[180:183], v[4:7]
	v_mfma_f32_16x16x32_bf16 v[36:39], v[206:209], v[180:183], v[36:39]
	v_lshl_add_u64 v[230:231], v[144:145], 0, s[2:3]
	s_add_i32 s17, s16, 0x4000
	s_mov_b32 m0, s17
	s_nop 0
	global_load_lds_dwordx4 v[230:231], off
	v_mfma_f32_16x16x32_bf16 v[68:71], v[210:213], v[180:183], v[68:71]
	v_mfma_f32_16x16x32_bf16 v[100:103], v[214:217], v[180:183], v[100:103]
	s_waitcnt lgkmcnt(1)
	v_mfma_f32_16x16x32_bf16 v[8:11], v[202:205], v[222:225], v[8:11]
	v_mfma_f32_16x16x32_bf16 v[40:43], v[206:209], v[222:225], v[40:43]
	v_lshl_add_u64 v[230:231], v[142:143], 0, s[2:3]
	s_add_i32 s17, s16, 0x6000
	s_mov_b32 m0, s17
	s_nop 0
	global_load_lds_dwordx4 v[230:231], off
	v_mfma_f32_16x16x32_bf16 v[72:75], v[210:213], v[222:225], v[72:75]
	v_mfma_f32_16x16x32_bf16 v[104:107], v[214:217], v[222:225], v[104:107]
	s_waitcnt lgkmcnt(0)
	v_mfma_f32_16x16x32_bf16 v[12:15], v[202:205], v[226:229], v[12:15]
	v_mfma_f32_16x16x32_bf16 v[44:47], v[206:209], v[226:229], v[44:47]
	v_lshl_add_u64 v[230:231], v[140:141], 0, s[2:3]
	s_add_i32 s17, s16, 0x8000
	s_mov_b32 m0, s17
	s_nop 0
	global_load_lds_dwordx4 v[230:231], off
	v_mfma_f32_16x16x32_bf16 v[76:79], v[210:213], v[226:229], v[76:79]
	v_mfma_f32_16x16x32_bf16 v[108:111], v[214:217], v[226:229], v[108:111]
	ds_read_b128 v[218:221], v238 offset:8192
	ds_read_b128 v[180:183], v238 offset:10240
	ds_read_b128 v[222:225], v238 offset:12288
	ds_read_b128 v[226:229], v238 offset:14336
	s_waitcnt lgkmcnt(3)
	v_mfma_f32_16x16x32_bf16 v[16:19], v[202:205], v[218:221], v[16:19]
	v_mfma_f32_16x16x32_bf16 v[48:51], v[206:209], v[218:221], v[48:51]
	v_lshl_add_u64 v[230:231], v[138:139], 0, s[2:3]
	s_add_i32 s17, s16, 0xa000
	s_mov_b32 m0, s17
	s_nop 0
	global_load_lds_dwordx4 v[230:231], off
	v_mfma_f32_16x16x32_bf16 v[80:83], v[210:213], v[218:221], v[80:83]
	v_mfma_f32_16x16x32_bf16 v[112:115], v[214:217], v[218:221], v[112:115]
	s_waitcnt lgkmcnt(2)
	v_mfma_f32_16x16x32_bf16 v[20:23], v[202:205], v[180:183], v[20:23]
	v_mfma_f32_16x16x32_bf16 v[52:55], v[206:209], v[180:183], v[52:55]
	v_lshl_add_u64 v[230:231], v[136:137], 0, s[2:3]
	s_add_i32 s17, s16, 0xc000
	s_mov_b32 m0, s17
	s_nop 0
	global_load_lds_dwordx4 v[230:231], off
	v_mfma_f32_16x16x32_bf16 v[84:87], v[210:213], v[180:183], v[84:87]
	v_mfma_f32_16x16x32_bf16 v[116:119], v[214:217], v[180:183], v[116:119]
	s_waitcnt lgkmcnt(1)
	v_mfma_f32_16x16x32_bf16 v[24:27], v[202:205], v[222:225], v[24:27]
	v_mfma_f32_16x16x32_bf16 v[56:59], v[206:209], v[222:225], v[56:59]
	v_lshl_add_u64 v[230:231], v[134:135], 0, s[2:3]
	s_add_i32 s17, s16, 0xe000
	s_mov_b32 m0, s17
	s_nop 0
	global_load_lds_dwordx4 v[230:231], off
	s_add_u32 s2, s2, 0x80
	s_addc_u32 s3, s3, 0
	s_cmpk_eq_i32 s2, 0x780
	v_mfma_f32_16x16x32_bf16 v[88:91], v[210:213], v[222:225], v[88:91]
	v_mfma_f32_16x16x32_bf16 v[120:123], v[214:217], v[222:225], v[120:123]
	s_waitcnt lgkmcnt(0)
	v_mfma_f32_16x16x32_bf16 v[28:31], v[202:205], v[226:229], v[28:31]
	v_mfma_f32_16x16x32_bf16 v[60:63], v[206:209], v[226:229], v[60:63]
	v_mfma_f32_16x16x32_bf16 v[92:95], v[210:213], v[226:229], v[92:95]
	v_mfma_f32_16x16x32_bf16 v[124:127], v[214:217], v[226:229], v[124:127]
	v_xor_b32_e32 v239, 64, v237
	v_add_u32_e32 v239, s0, v239
	ds_read_b128 v[202:205], v239
	ds_read_b128 v[206:209], v239 offset:2048
	ds_read_b128 v[210:213], v239 offset:4096
	ds_read_b128 v[214:217], v239 offset:6144
	v_xor_b32_e32 v238, 64, v236
	v_add_u32_e32 v238, s0, v238
	ds_read_b128 v[218:221], v238
	ds_read_b128 v[180:183], v238 offset:2048
	ds_read_b128 v[222:225], v238 offset:4096
	ds_read_b128 v[226:229], v238 offset:6144
	s_waitcnt lgkmcnt(3)
	v_mfma_f32_16x16x32_bf16 v[0:3], v[202:205], v[218:221], v[0:3]
	v_mfma_f32_16x16x32_bf16 v[32:35], v[206:209], v[218:221], v[32:35]
	v_mfma_f32_16x16x32_bf16 v[64:67], v[210:213], v[218:221], v[64:67]
	v_mfma_f32_16x16x32_bf16 v[96:99], v[214:217], v[218:221], v[96:99]
	s_waitcnt lgkmcnt(2)
	v_mfma_f32_16x16x32_bf16 v[4:7], v[202:205], v[180:183], v[4:7]
	v_mfma_f32_16x16x32_bf16 v[36:39], v[206:209], v[180:183], v[36:39]
	v_mfma_f32_16x16x32_bf16 v[68:71], v[210:213], v[180:183], v[68:71]
	v_mfma_f32_16x16x32_bf16 v[100:103], v[214:217], v[180:183], v[100:103]
	s_waitcnt lgkmcnt(1)
	v_mfma_f32_16x16x32_bf16 v[8:11], v[202:205], v[222:225], v[8:11]
	v_mfma_f32_16x16x32_bf16 v[40:43], v[206:209], v[222:225], v[40:43]
	v_mfma_f32_16x16x32_bf16 v[72:75], v[210:213], v[222:225], v[72:75]
	v_mfma_f32_16x16x32_bf16 v[104:107], v[214:217], v[222:225], v[104:107]
	s_waitcnt lgkmcnt(0)
	v_mfma_f32_16x16x32_bf16 v[12:15], v[202:205], v[226:229], v[12:15]
	v_mfma_f32_16x16x32_bf16 v[44:47], v[206:209], v[226:229], v[44:47]
	v_mfma_f32_16x16x32_bf16 v[76:79], v[210:213], v[226:229], v[76:79]
	v_mfma_f32_16x16x32_bf16 v[108:111], v[214:217], v[226:229], v[108:111]
	ds_read_b128 v[218:221], v238 offset:8192
	ds_read_b128 v[180:183], v238 offset:10240
	ds_read_b128 v[222:225], v238 offset:12288
	ds_read_b128 v[226:229], v238 offset:14336
	s_waitcnt lgkmcnt(3)
	v_mfma_f32_16x16x32_bf16 v[16:19], v[202:205], v[218:221], v[16:19]
	v_mfma_f32_16x16x32_bf16 v[48:51], v[206:209], v[218:221], v[48:51]
	v_mfma_f32_16x16x32_bf16 v[80:83], v[210:213], v[218:221], v[80:83]
	v_mfma_f32_16x16x32_bf16 v[112:115], v[214:217], v[218:221], v[112:115]
	s_waitcnt lgkmcnt(2)
	v_mfma_f32_16x16x32_bf16 v[20:23], v[202:205], v[180:183], v[20:23]
	v_mfma_f32_16x16x32_bf16 v[52:55], v[206:209], v[180:183], v[52:55]
	v_mfma_f32_16x16x32_bf16 v[84:87], v[210:213], v[180:183], v[84:87]
	v_mfma_f32_16x16x32_bf16 v[116:119], v[214:217], v[180:183], v[116:119]
	s_waitcnt lgkmcnt(1)
	v_mfma_f32_16x16x32_bf16 v[24:27], v[202:205], v[222:225], v[24:27]
	v_mfma_f32_16x16x32_bf16 v[56:59], v[206:209], v[222:225], v[56:59]
	v_mfma_f32_16x16x32_bf16 v[88:91], v[210:213], v[222:225], v[88:91]
	v_mfma_f32_16x16x32_bf16 v[120:123], v[214:217], v[222:225], v[120:123]
	s_waitcnt lgkmcnt(0)
	v_mfma_f32_16x16x32_bf16 v[28:31], v[202:205], v[226:229], v[28:31]
	v_mfma_f32_16x16x32_bf16 v[60:63], v[206:209], v[226:229], v[60:63]
	v_mfma_f32_16x16x32_bf16 v[92:95], v[210:213], v[226:229], v[92:95]
	v_mfma_f32_16x16x32_bf16 v[124:127], v[214:217], v[226:229], v[124:127]
	s_mov_b32 s0, s1
	s_cbranch_scc0 .LBB0_745
	s_waitcnt vmcnt(0)
	s_barrier
	v_mov_b32_e32 v133, 0x358637bd
	s_and_saveexec_b64 s[2:3], s[6:7]
	s_cbranch_execz .LBB0_748
	v_add_u32_e32 v134, s19, v150
	v_ashrrev_i32_e32 v135, 31, v134
	v_lshlrev_b64 v[134:135], 6, v[134:135]
	v_lshl_add_u64 v[146:147], s[12:13], 0, v[134:135]
	global_load_dwordx4 v[134:137], v[146:147], off
	global_load_dwordx4 v[138:141], v[146:147], off offset:16
	global_load_dwordx4 v[142:145], v[146:147], off offset:32
	s_nop 0
	global_load_dwordx4 v[146:149], v[146:147], off offset:48
	s_waitcnt vmcnt(3)
	v_mov_b32_e32 v180, v135
	v_mov_b32_e32 v181, v136
	v_mov_b32_e32 v135, v137
	v_pk_add_f32 v[134:135], v[180:181], v[134:135]
	s_waitcnt vmcnt(2)
	v_mov_b32_e32 v182, v139
	v_mov_b32_e32 v183, v140
	v_mov_b32_e32 v139, v141
	v_add_f32_e32 v133, 0, v134
	v_pk_add_f32 v[136:137], v[182:183], v[138:139]
	v_add_f32_e32 v133, v133, v135
	s_waitcnt vmcnt(1)
	v_mov_b32_e32 v202, v143
	v_mov_b32_e32 v203, v144
	v_mov_b32_e32 v143, v145
	v_add_f32_e32 v133, v133, v136
	v_pk_add_f32 v[138:139], v[202:203], v[142:143]
	v_add_f32_e32 v133, v133, v137
	s_waitcnt vmcnt(0)
	v_mov_b32_e32 v204, v147
	v_mov_b32_e32 v205, v148
	v_mov_b32_e32 v147, v149
	v_add_f32_e32 v133, v133, v138
	v_add_f32_e32 v133, v133, v139
	v_pk_add_f32 v[134:135], v[204:205], v[146:147]
	s_nop 0
	v_add_f32_e32 v133, v133, v134
	v_add_f32_e32 v133, v133, v135
	v_fmamk_f32 v133, v133, 0x3a800000, v187

.LBB0_750:
	v_add_u32_e32 v239, 0x10010, v237
	ds_read_b128 v[202:205], v239
	ds_read_b128 v[206:209], v239 offset:2048
	ds_read_b128 v[210:213], v239 offset:4096
	ds_read_b128 v[214:217], v239 offset:6144
	v_add_u32_e32 v238, 0x10010, v236
	ds_read_b128 v[218:221], v238
	ds_read_b128 v[180:183], v238 offset:2048
	ds_read_b128 v[222:225], v238 offset:4096
	ds_read_b128 v[226:229], v238 offset:6144
	s_waitcnt lgkmcnt(3)
	v_mfma_f32_16x16x32_bf16 v[0:3], v[202:205], v[218:221], v[0:3]
	v_mfma_f32_16x16x32_bf16 v[32:35], v[206:209], v[218:221], v[32:35]
	v_mfma_f32_16x16x32_bf16 v[64:67], v[210:213], v[218:221], v[64:67]
	v_mfma_f32_16x16x32_bf16 v[96:99], v[214:217], v[218:221], v[96:99]
	s_waitcnt lgkmcnt(2)
	v_mfma_f32_16x16x32_bf16 v[4:7], v[202:205], v[180:183], v[4:7]
	v_mfma_f32_16x16x32_bf16 v[36:39], v[206:209], v[180:183], v[36:39]
	v_mfma_f32_16x16x32_bf16 v[68:71], v[210:213], v[180:183], v[68:71]
	v_mfma_f32_16x16x32_bf16 v[100:103], v[214:217], v[180:183], v[100:103]
	s_waitcnt lgkmcnt(1)
	v_mfma_f32_16x16x32_bf16 v[8:11], v[202:205], v[222:225], v[8:11]
	v_mfma_f32_16x16x32_bf16 v[40:43], v[206:209], v[222:225], v[40:43]
	v_mfma_f32_16x16x32_bf16 v[72:75], v[210:213], v[222:225], v[72:75]
	v_mfma_f32_16x16x32_bf16 v[104:107], v[214:217], v[222:225], v[104:107]
	s_waitcnt lgkmcnt(0)
	v_mfma_f32_16x16x32_bf16 v[12:15], v[202:205], v[226:229], v[12:15]
	v_mfma_f32_16x16x32_bf16 v[44:47], v[206:209], v[226:229], v[44:47]
	v_mfma_f32_16x16x32_bf16 v[76:79], v[210:213], v[226:229], v[76:79]
	v_mfma_f32_16x16x32_bf16 v[108:111], v[214:217], v[226:229], v[108:111]
	ds_read_b128 v[218:221], v238 offset:8192
	ds_read_b128 v[180:183], v238 offset:10240
	ds_read_b128 v[222:225], v238 offset:12288
	ds_read_b128 v[226:229], v238 offset:14336
	s_waitcnt lgkmcnt(3)
	v_mfma_f32_16x16x32_bf16 v[16:19], v[202:205], v[218:221], v[16:19]
	v_mfma_f32_16x16x32_bf16 v[48:51], v[206:209], v[218:221], v[48:51]
	v_mfma_f32_16x16x32_bf16 v[80:83], v[210:213], v[218:221], v[80:83]
	v_mfma_f32_16x16x32_bf16 v[112:115], v[214:217], v[218:221], v[112:115]
	s_waitcnt lgkmcnt(2)
	v_mfma_f32_16x16x32_bf16 v[20:23], v[202:205], v[180:183], v[20:23]
	v_mfma_f32_16x16x32_bf16 v[52:55], v[206:209], v[180:183], v[52:55]
	v_mfma_f32_16x16x32_bf16 v[84:87], v[210:213], v[180:183], v[84:87]
	v_mfma_f32_16x16x32_bf16 v[116:119], v[214:217], v[180:183], v[116:119]
	s_waitcnt lgkmcnt(1)
	v_mfma_f32_16x16x32_bf16 v[24:27], v[202:205], v[222:225], v[24:27]
	v_mfma_f32_16x16x32_bf16 v[56:59], v[206:209], v[222:225], v[56:59]
	v_mfma_f32_16x16x32_bf16 v[88:91], v[210:213], v[222:225], v[88:91]
	v_mfma_f32_16x16x32_bf16 v[120:123], v[214:217], v[222:225], v[120:123]
	s_waitcnt lgkmcnt(0)
	v_mfma_f32_16x16x32_bf16 v[28:31], v[202:205], v[226:229], v[28:31]
	v_mfma_f32_16x16x32_bf16 v[60:63], v[206:209], v[226:229], v[60:63]
	v_mfma_f32_16x16x32_bf16 v[92:95], v[210:213], v[226:229], v[92:95]
	v_mfma_f32_16x16x32_bf16 v[124:127], v[214:217], v[226:229], v[124:127]
	v_xor_b32_e32 v239, 64, v237
	v_add_u32_e32 v239, 0x10010, v239
	ds_read_b128 v[202:205], v239
	ds_read_b128 v[206:209], v239 offset:2048
	ds_read_b128 v[210:213], v239 offset:4096
	ds_read_b128 v[214:217], v239 offset:6144
	v_xor_b32_e32 v238, 64, v236
	v_add_u32_e32 v238, 0x10010, v238
	ds_read_b128 v[218:221], v238
	ds_read_b128 v[180:183], v238 offset:2048
	ds_read_b128 v[222:225], v238 offset:4096
	ds_read_b128 v[226:229], v238 offset:6144
	s_waitcnt lgkmcnt(3)
	v_mfma_f32_16x16x32_bf16 v[0:3], v[202:205], v[218:221], v[0:3]
	v_mfma_f32_16x16x32_bf16 v[32:35], v[206:209], v[218:221], v[32:35]
	v_mfma_f32_16x16x32_bf16 v[64:67], v[210:213], v[218:221], v[64:67]
	v_mfma_f32_16x16x32_bf16 v[96:99], v[214:217], v[218:221], v[96:99]
	s_waitcnt lgkmcnt(2)
	v_mfma_f32_16x16x32_bf16 v[4:7], v[202:205], v[180:183], v[4:7]
	v_mfma_f32_16x16x32_bf16 v[36:39], v[206:209], v[180:183], v[36:39]
	v_mfma_f32_16x16x32_bf16 v[68:71], v[210:213], v[180:183], v[68:71]
	v_mfma_f32_16x16x32_bf16 v[100:103], v[214:217], v[180:183], v[100:103]
	s_waitcnt lgkmcnt(1)
	v_mfma_f32_16x16x32_bf16 v[8:11], v[202:205], v[222:225], v[8:11]
	v_mfma_f32_16x16x32_bf16 v[40:43], v[206:209], v[222:225], v[40:43]
	v_mfma_f32_16x16x32_bf16 v[72:75], v[210:213], v[222:225], v[72:75]
	v_mfma_f32_16x16x32_bf16 v[104:107], v[214:217], v[222:225], v[104:107]
	s_waitcnt lgkmcnt(0)
	v_mfma_f32_16x16x32_bf16 v[12:15], v[202:205], v[226:229], v[12:15]
	v_mfma_f32_16x16x32_bf16 v[44:47], v[206:209], v[226:229], v[44:47]
	v_mfma_f32_16x16x32_bf16 v[76:79], v[210:213], v[226:229], v[76:79]
	v_mfma_f32_16x16x32_bf16 v[108:111], v[214:217], v[226:229], v[108:111]
	ds_read_b128 v[218:221], v238 offset:8192
	ds_read_b128 v[180:183], v238 offset:10240
	ds_read_b128 v[222:225], v238 offset:12288
	ds_read_b128 v[226:229], v238 offset:14336
	s_waitcnt lgkmcnt(3)
	v_mfma_f32_16x16x32_bf16 v[16:19], v[202:205], v[218:221], v[16:19]
	v_mfma_f32_16x16x32_bf16 v[48:51], v[206:209], v[218:221], v[48:51]
	v_mfma_f32_16x16x32_bf16 v[80:83], v[210:213], v[218:221], v[80:83]
	v_mfma_f32_16x16x32_bf16 v[112:115], v[214:217], v[218:221], v[112:115]
	s_waitcnt lgkmcnt(2)
	v_mfma_f32_16x16x32_bf16 v[20:23], v[202:205], v[180:183], v[20:23]
	v_mfma_f32_16x16x32_bf16 v[52:55], v[206:209], v[180:183], v[52:55]
	v_mfma_f32_16x16x32_bf16 v[84:87], v[210:213], v[180:183], v[84:87]
	v_mfma_f32_16x16x32_bf16 v[116:119], v[214:217], v[180:183], v[116:119]
	s_waitcnt lgkmcnt(1)
	v_mfma_f32_16x16x32_bf16 v[24:27], v[202:205], v[222:225], v[24:27]
	v_mfma_f32_16x16x32_bf16 v[56:59], v[206:209], v[222:225], v[56:59]
	v_mfma_f32_16x16x32_bf16 v[88:91], v[210:213], v[222:225], v[88:91]
	v_mfma_f32_16x16x32_bf16 v[120:123], v[214:217], v[222:225], v[120:123]
	s_waitcnt lgkmcnt(0)
	v_mfma_f32_16x16x32_bf16 v[28:31], v[202:205], v[226:229], v[28:31]
	v_mfma_f32_16x16x32_bf16 v[60:63], v[206:209], v[226:229], v[60:63]
	v_mfma_f32_16x16x32_bf16 v[92:95], v[210:213], v[226:229], v[92:95]
	v_mfma_f32_16x16x32_bf16 v[124:127], v[214:217], v[226:229], v[124:127]
	s_and_saveexec_b64 s[2:3], s[6:7]
	s_cbranch_execz .LBB0_752
	v_mul_f32_e32 v134, 0x4b800000, v133
	v_cmp_gt_f32_e32 vcc, s28, v133
	s_nop 1
	v_cndmask_b32_e32 v133, v133, v134, vcc
	v_rsq_f32_e32 v133, v133
	s_nop 0
	v_mul_f32_e32 v134, 0x45800000, v133
	v_cndmask_b32_e32 v133, v133, v134, vcc
	ds_write_b32 v162, v133
.LBB0_752:
	s_or_b64 exec, exec, s[2:3]
	s_waitcnt lgkmcnt(0)
	s_barrier
	v_and_b32_e32 v133, 15, v150
	v_bfe_u32 v134, v150, 4, 2
	v_lshrrev_b32_e32 v135, 6, v150
	v_lshrrev_b32_e32 v136, 8, v150
	v_and_b32_e32 v137, 3, v135
	v_lshl_add_u32 v143, v136, 7, v133
	v_lshlrev_b32_e32 v138, 2, v143
	v_add_u32_e32 v138, 0x20010, v138
	v_lshlrev_b32_e32 v139, 4, v143
	v_add_u32_e32 v139, 0x20410, v139
	v_lshl_add_u32 v140, v137, 2, v139
	v_add_u32_e32 v141, 0x1000, v139
	v_add_u32_e32 v142, 0x1000, v140
	v_and_b32_e32 v143, 63, v150
	v_cmp_gt_u32_e64 s[46:47], 16, v143
	ds_read2_b32 v[180:181], v138 offset0:0 offset1:16
	ds_read2_b32 v[182:183], v138 offset0:32 offset1:48
	ds_read2_b32 v[202:203], v138 offset0:64 offset1:80
	ds_read2_b32 v[204:205], v138 offset0:96 offset1:112
	s_nop 7
	s_waitcnt lgkmcnt(0)
	v_mul_f32_e32 v0, v0, v180
	v_mul_f32_e32 v1, v1, v180
	v_mul_f32_e32 v2, v2, v180
	v_mul_f32_e32 v3, v3, v180
	v_mul_f32_e32 v32, v32, v180
	v_mul_f32_e32 v33, v33, v180
	v_mul_f32_e32 v34, v34, v180
	v_mul_f32_e32 v35, v35, v180
	v_mul_f32_e32 v64, v64, v180
	v_mul_f32_e32 v65, v65, v180
	v_mul_f32_e32 v66, v66, v180
	v_mul_f32_e32 v67, v67, v180
	v_mul_f32_e32 v96, v96, v180
	v_mul_f32_e32 v97, v97, v180
	v_mul_f32_e32 v98, v98, v180
	v_mul_f32_e32 v99, v99, v180
	v_max3_f32 v206, v0, v1, v2
	v_max3_f32 v206, v206, v3, v32
	v_max3_f32 v206, v206, v33, v34
	v_max3_f32 v206, v206, v35, v64
	v_max3_f32 v206, v206, v65, v66
	v_max3_f32 v206, v206, v67, v96
	v_max3_f32 v206, v206, v97, v98
	v_max_f32_e32 v206, v206, v99
	v_mov_b32_e32 v143, v206
	v_mov_b32_e32 v144, v206
	s_nop 1
	v_permlane16_swap_b32_e32 v143, v144
	v_max_f32_e32 v206, v143, v144
	v_mov_b32_e32 v143, v206
	v_mov_b32_e32 v144, v206
	s_nop 1
	v_permlane32_swap_b32_e32 v143, v144
	v_max_f32_e32 v206, v143, v144
	v_mul_f32_e32 v4, v4, v181
	v_mul_f32_e32 v5, v5, v181
	v_mul_f32_e32 v6, v6, v181
	v_mul_f32_e32 v7, v7, v181
	v_mul_f32_e32 v36, v36, v181
	v_mul_f32_e32 v37, v37, v181
	v_mul_f32_e32 v38, v38, v181
	v_mul_f32_e32 v39, v39, v181
	v_mul_f32_e32 v68, v68, v181
	v_mul_f32_e32 v69, v69, v181
	v_mul_f32_e32 v70, v70, v181
	v_mul_f32_e32 v71, v71, v181
	v_mul_f32_e32 v100, v100, v181
	v_mul_f32_e32 v101, v101, v181
	v_mul_f32_e32 v102, v102, v181
	v_mul_f32_e32 v103, v103, v181
	v_max3_f32 v207, v4, v5, v6
	v_max3_f32 v207, v207, v7, v36
	v_max3_f32 v207, v207, v37, v38
	v_max3_f32 v207, v207, v39, v68
	v_max3_f32 v207, v207, v69, v70
	v_max3_f32 v207, v207, v71, v100
	v_max3_f32 v207, v207, v101, v102
	v_max_f32_e32 v207, v207, v103
	v_mov_b32_e32 v143, v207
	v_mov_b32_e32 v144, v207
	s_nop 1
	v_permlane16_swap_b32_e32 v143, v144
	v_max_f32_e32 v207, v143, v144
	v_mov_b32_e32 v143, v207
	v_mov_b32_e32 v144, v207
	s_nop 1
	v_permlane32_swap_b32_e32 v143, v144
	v_max_f32_e32 v207, v143, v144
	v_mul_f32_e32 v8, v8, v182
	v_mul_f32_e32 v9, v9, v182
	v_mul_f32_e32 v10, v10, v182
	v_mul_f32_e32 v11, v11, v182
	v_mul_f32_e32 v40, v40, v182
	v_mul_f32_e32 v41, v41, v182
	v_mul_f32_e32 v42, v42, v182
	v_mul_f32_e32 v43, v43, v182
	v_mul_f32_e32 v72, v72, v182
	v_mul_f32_e32 v73, v73, v182
	v_mul_f32_e32 v74, v74, v182
	v_mul_f32_e32 v75, v75, v182
	v_mul_f32_e32 v104, v104, v182
	v_mul_f32_e32 v105, v105, v182
	v_mul_f32_e32 v106, v106, v182
	v_mul_f32_e32 v107, v107, v182
	v_max3_f32 v208, v8, v9, v10
	v_max3_f32 v208, v208, v11, v40
	v_max3_f32 v208, v208, v41, v42
	v_max3_f32 v208, v208, v43, v72
	v_max3_f32 v208, v208, v73, v74
	v_max3_f32 v208, v208, v75, v104
	v_max3_f32 v208, v208, v105, v106
	v_max_f32_e32 v208, v208, v107
	v_mov_b32_e32 v143, v208
	v_mov_b32_e32 v144, v208
	s_nop 1
	v_permlane16_swap_b32_e32 v143, v144
	v_max_f32_e32 v208, v143, v144
	v_mov_b32_e32 v143, v208
	v_mov_b32_e32 v144, v208
	s_nop 1
	v_permlane32_swap_b32_e32 v143, v144
	v_max_f32_e32 v208, v143, v144
	v_mul_f32_e32 v12, v12, v183
	v_mul_f32_e32 v13, v13, v183
	v_mul_f32_e32 v14, v14, v183
	v_mul_f32_e32 v15, v15, v183
	v_mul_f32_e32 v44, v44, v183
	v_mul_f32_e32 v45, v45, v183
	v_mul_f32_e32 v46, v46, v183
	v_mul_f32_e32 v47, v47, v183
	v_mul_f32_e32 v76, v76, v183
	v_mul_f32_e32 v77, v77, v183
	v_mul_f32_e32 v78, v78, v183
	v_mul_f32_e32 v79, v79, v183
	v_mul_f32_e32 v108, v108, v183
	v_mul_f32_e32 v109, v109, v183
	v_mul_f32_e32 v110, v110, v183
	v_mul_f32_e32 v111, v111, v183
	v_max3_f32 v209, v12, v13, v14
	v_max3_f32 v209, v209, v15, v44
	v_max3_f32 v209, v209, v45, v46
	v_max3_f32 v209, v209, v47, v76
	v_max3_f32 v209, v209, v77, v78
	v_max3_f32 v209, v209, v79, v108
	v_max3_f32 v209, v209, v109, v110
	v_max_f32_e32 v209, v209, v111
	v_mov_b32_e32 v143, v209
	v_mov_b32_e32 v144, v209
	s_nop 1
	v_permlane16_swap_b32_e32 v143, v144
	v_max_f32_e32 v209, v143, v144
	v_mov_b32_e32 v143, v209
	v_mov_b32_e32 v144, v209
	s_nop 1
	v_permlane32_swap_b32_e32 v143, v144
	v_max_f32_e32 v209, v143, v144
	v_mul_f32_e32 v16, v16, v202
	v_mul_f32_e32 v17, v17, v202
	v_mul_f32_e32 v18, v18, v202
	v_mul_f32_e32 v19, v19, v202
	v_mul_f32_e32 v48, v48, v202
	v_mul_f32_e32 v49, v49, v202
	v_mul_f32_e32 v50, v50, v202
	v_mul_f32_e32 v51, v51, v202
	v_mul_f32_e32 v80, v80, v202
	v_mul_f32_e32 v81, v81, v202
	v_mul_f32_e32 v82, v82, v202
	v_mul_f32_e32 v83, v83, v202
	v_mul_f32_e32 v112, v112, v202
	v_mul_f32_e32 v113, v113, v202
	v_mul_f32_e32 v114, v114, v202
	v_mul_f32_e32 v115, v115, v202
	v_max3_f32 v210, v16, v17, v18
	v_max3_f32 v210, v210, v19, v48
	v_max3_f32 v210, v210, v49, v50
	v_max3_f32 v210, v210, v51, v80
	v_max3_f32 v210, v210, v81, v82
	v_max3_f32 v210, v210, v83, v112
	v_max3_f32 v210, v210, v113, v114
	v_max_f32_e32 v210, v210, v115
	v_mov_b32_e32 v143, v210
	v_mov_b32_e32 v144, v210
	s_nop 1
	v_permlane16_swap_b32_e32 v143, v144
	v_max_f32_e32 v210, v143, v144
	v_mov_b32_e32 v143, v210
	v_mov_b32_e32 v144, v210
	s_nop 1
	v_permlane32_swap_b32_e32 v143, v144
	v_max_f32_e32 v210, v143, v144
	v_mul_f32_e32 v20, v20, v203
	v_mul_f32_e32 v21, v21, v203
	v_mul_f32_e32 v22, v22, v203
	v_mul_f32_e32 v23, v23, v203
	v_mul_f32_e32 v52, v52, v203
	v_mul_f32_e32 v53, v53, v203
	v_mul_f32_e32 v54, v54, v203
	v_mul_f32_e32 v55, v55, v203
	v_mul_f32_e32 v84, v84, v203
	v_mul_f32_e32 v85, v85, v203
	v_mul_f32_e32 v86, v86, v203
	v_mul_f32_e32 v87, v87, v203
	v_mul_f32_e32 v116, v116, v203
	v_mul_f32_e32 v117, v117, v203
	v_mul_f32_e32 v118, v118, v203
	v_mul_f32_e32 v119, v119, v203
	v_max3_f32 v211, v20, v21, v22
	v_max3_f32 v211, v211, v23, v52
	v_max3_f32 v211, v211, v53, v54
	v_max3_f32 v211, v211, v55, v84
	v_max3_f32 v211, v211, v85, v86
	v_max3_f32 v211, v211, v87, v116
	v_max3_f32 v211, v211, v117, v118
	v_max_f32_e32 v211, v211, v119
	v_mov_b32_e32 v143, v211
	v_mov_b32_e32 v144, v211
	s_nop 1
	v_permlane16_swap_b32_e32 v143, v144
	v_max_f32_e32 v211, v143, v144
	v_mov_b32_e32 v143, v211
	v_mov_b32_e32 v144, v211
	s_nop 1
	v_permlane32_swap_b32_e32 v143, v144
	v_max_f32_e32 v211, v143, v144
	v_mul_f32_e32 v24, v24, v204
	v_mul_f32_e32 v25, v25, v204
	v_mul_f32_e32 v26, v26, v204
	v_mul_f32_e32 v27, v27, v204
	v_mul_f32_e32 v56, v56, v204
	v_mul_f32_e32 v57, v57, v204
	v_mul_f32_e32 v58, v58, v204
	v_mul_f32_e32 v59, v59, v204
	v_mul_f32_e32 v88, v88, v204
	v_mul_f32_e32 v89, v89, v204
	v_mul_f32_e32 v90, v90, v204
	v_mul_f32_e32 v91, v91, v204
	v_mul_f32_e32 v120, v120, v204
	v_mul_f32_e32 v121, v121, v204
	v_mul_f32_e32 v122, v122, v204
	v_mul_f32_e32 v123, v123, v204
	v_max3_f32 v212, v24, v25, v26
	v_max3_f32 v212, v212, v27, v56
	v_max3_f32 v212, v212, v57, v58
	v_max3_f32 v212, v212, v59, v88
	v_max3_f32 v212, v212, v89, v90
	v_max3_f32 v212, v212, v91, v120
	v_max3_f32 v212, v212, v121, v122
	v_max_f32_e32 v212, v212, v123
	v_mov_b32_e32 v143, v212
	v_mov_b32_e32 v144, v212
	s_nop 1
	v_permlane16_swap_b32_e32 v143, v144
	v_max_f32_e32 v212, v143, v144
	v_mov_b32_e32 v143, v212
	v_mov_b32_e32 v144, v212
	s_nop 1
	v_permlane32_swap_b32_e32 v143, v144
	v_max_f32_e32 v212, v143, v144
	v_mul_f32_e32 v28, v28, v205
	v_mul_f32_e32 v29, v29, v205
	v_mul_f32_e32 v30, v30, v205
	v_mul_f32_e32 v31, v31, v205
	v_mul_f32_e32 v60, v60, v205
	v_mul_f32_e32 v61, v61, v205
	v_mul_f32_e32 v62, v62, v205
	v_mul_f32_e32 v63, v63, v205
	v_mul_f32_e32 v92, v92, v205
	v_mul_f32_e32 v93, v93, v205
	v_mul_f32_e32 v94, v94, v205
	v_mul_f32_e32 v95, v95, v205
	v_mul_f32_e32 v124, v124, v205
	v_mul_f32_e32 v125, v125, v205
	v_mul_f32_e32 v126, v126, v205
	v_mul_f32_e32 v127, v127, v205
	v_max3_f32 v213, v28, v29, v30
	v_max3_f32 v213, v213, v31, v60
	v_max3_f32 v213, v213, v61, v62
	v_max3_f32 v213, v213, v63, v92
	v_max3_f32 v213, v213, v93, v94
	v_max3_f32 v213, v213, v95, v124
	v_max3_f32 v213, v213, v125, v126
	v_max_f32_e32 v213, v213, v127
	v_mov_b32_e32 v143, v213
	v_mov_b32_e32 v144, v213
	s_nop 1
	v_permlane16_swap_b32_e32 v143, v144
	v_max_f32_e32 v213, v143, v144
	v_mov_b32_e32 v143, v213
	v_mov_b32_e32 v144, v213
	s_nop 1
	v_permlane32_swap_b32_e32 v143, v144
	v_max_f32_e32 v213, v143, v144
	s_and_saveexec_b64 s[72:73], s[46:47]
	ds_write_b32 v140, v206
	ds_write_b32 v140, v207 offset:256
	ds_write_b32 v140, v208 offset:512
	ds_write_b32 v140, v209 offset:768
	ds_write_b32 v140, v210 offset:1024
	ds_write_b32 v140, v211 offset:1280
	ds_write_b32 v140, v212 offset:1536
	ds_write_b32 v140, v213 offset:1792
	s_or_b64 exec, exec, s[72:73]
	s_waitcnt lgkmcnt(0)
	s_barrier
	ds_read_b128 v[214:217], v139
	ds_read_b128 v[218:221], v139 offset:256
	ds_read_b128 v[222:225], v139 offset:512
	ds_read_b128 v[226:229], v139 offset:768
	ds_read_b128 v[236:239], v139 offset:1024
	ds_read_b128 v[240:243], v139 offset:1280
	ds_read_b128 v[248:251], v139 offset:1536
	ds_read_b128 v[146:149], v139 offset:1792
	s_waitcnt lgkmcnt(7)
	v_max3_f32 v206, v214, v215, v216
	v_max_f32_e32 v206, v206, v217
	s_waitcnt lgkmcnt(6)
	v_max3_f32 v207, v218, v219, v220
	v_max_f32_e32 v207, v207, v221
	s_waitcnt lgkmcnt(5)
	v_max3_f32 v208, v222, v223, v224
	v_max_f32_e32 v208, v208, v225
	s_waitcnt lgkmcnt(4)
	v_max3_f32 v209, v226, v227, v228
	v_max_f32_e32 v209, v209, v229
	s_waitcnt lgkmcnt(3)
	v_max3_f32 v210, v236, v237, v238
	v_max_f32_e32 v210, v210, v239
	s_waitcnt lgkmcnt(2)
	v_max3_f32 v211, v240, v241, v242
	v_max_f32_e32 v211, v211, v243
	s_waitcnt lgkmcnt(1)
	v_max3_f32 v212, v248, v249, v250
	v_max_f32_e32 v212, v212, v251
	s_waitcnt lgkmcnt(0)
	v_max3_f32 v213, v146, v147, v148
	v_max_f32_e32 v213, v213, v149
	v_sub_f32_e32 v0, v0, v206
	v_sub_f32_e32 v1, v1, v206
	v_sub_f32_e32 v2, v2, v206
	v_sub_f32_e32 v3, v3, v206
	v_sub_f32_e32 v32, v32, v206
	v_sub_f32_e32 v33, v33, v206
	v_sub_f32_e32 v34, v34, v206
	v_sub_f32_e32 v35, v35, v206
	v_sub_f32_e32 v64, v64, v206
	v_sub_f32_e32 v65, v65, v206
	v_sub_f32_e32 v66, v66, v206
	v_sub_f32_e32 v67, v67, v206
	v_sub_f32_e32 v96, v96, v206
	v_sub_f32_e32 v97, v97, v206
	v_sub_f32_e32 v98, v98, v206
	v_sub_f32_e32 v99, v99, v206
	v_exp_f32_e32 v0, v0
	v_exp_f32_e32 v1, v1
	v_exp_f32_e32 v2, v2
	v_exp_f32_e32 v3, v3
	v_exp_f32_e32 v32, v32
	v_exp_f32_e32 v33, v33
	v_exp_f32_e32 v34, v34
	v_exp_f32_e32 v35, v35
	v_exp_f32_e32 v64, v64
	v_exp_f32_e32 v65, v65
	v_exp_f32_e32 v66, v66
	v_exp_f32_e32 v67, v67
	v_exp_f32_e32 v96, v96
	v_exp_f32_e32 v97, v97
	v_exp_f32_e32 v98, v98
	v_exp_f32_e32 v99, v99
	s_nop 0
	v_add_f32_e32 v206, v0, v1
	v_add_f32_e32 v206, v206, v2
	v_add_f32_e32 v206, v206, v3
	v_add_f32_e32 v206, v206, v32
	v_add_f32_e32 v206, v206, v33
	v_add_f32_e32 v206, v206, v34
	v_add_f32_e32 v206, v206, v35
	v_add_f32_e32 v206, v206, v64
	v_add_f32_e32 v206, v206, v65
	v_add_f32_e32 v206, v206, v66
	v_add_f32_e32 v206, v206, v67
	v_add_f32_e32 v206, v206, v96
	v_add_f32_e32 v206, v206, v97
	v_add_f32_e32 v206, v206, v98
	v_add_f32_e32 v206, v206, v99
	v_mov_b32_e32 v143, v206
	v_mov_b32_e32 v144, v206
	s_nop 1
	v_permlane16_swap_b32_e32 v143, v144
	v_add_f32_e32 v206, v143, v144
	v_mov_b32_e32 v143, v206
	v_mov_b32_e32 v144, v206
	s_nop 1
	v_permlane32_swap_b32_e32 v143, v144
	v_add_f32_e32 v206, v143, v144
	v_sub_f32_e32 v4, v4, v207
	v_sub_f32_e32 v5, v5, v207
	v_sub_f32_e32 v6, v6, v207
	v_sub_f32_e32 v7, v7, v207
	v_sub_f32_e32 v36, v36, v207
	v_sub_f32_e32 v37, v37, v207
	v_sub_f32_e32 v38, v38, v207
	v_sub_f32_e32 v39, v39, v207
	v_sub_f32_e32 v68, v68, v207
	v_sub_f32_e32 v69, v69, v207
	v_sub_f32_e32 v70, v70, v207
	v_sub_f32_e32 v71, v71, v207
	v_sub_f32_e32 v100, v100, v207
	v_sub_f32_e32 v101, v101, v207
	v_sub_f32_e32 v102, v102, v207
	v_sub_f32_e32 v103, v103, v207
	v_exp_f32_e32 v4, v4
	v_exp_f32_e32 v5, v5
	v_exp_f32_e32 v6, v6
	v_exp_f32_e32 v7, v7
	v_exp_f32_e32 v36, v36
	v_exp_f32_e32 v37, v37
	v_exp_f32_e32 v38, v38
	v_exp_f32_e32 v39, v39
	v_exp_f32_e32 v68, v68
	v_exp_f32_e32 v69, v69
	v_exp_f32_e32 v70, v70
	v_exp_f32_e32 v71, v71
	v_exp_f32_e32 v100, v100
	v_exp_f32_e32 v101, v101
	v_exp_f32_e32 v102, v102
	v_exp_f32_e32 v103, v103
	s_nop 0
	v_add_f32_e32 v207, v4, v5
	v_add_f32_e32 v207, v207, v6
	v_add_f32_e32 v207, v207, v7
	v_add_f32_e32 v207, v207, v36
	v_add_f32_e32 v207, v207, v37
	v_add_f32_e32 v207, v207, v38
	v_add_f32_e32 v207, v207, v39
	v_add_f32_e32 v207, v207, v68
	v_add_f32_e32 v207, v207, v69
	v_add_f32_e32 v207, v207, v70
	v_add_f32_e32 v207, v207, v71
	v_add_f32_e32 v207, v207, v100
	v_add_f32_e32 v207, v207, v101
	v_add_f32_e32 v207, v207, v102
	v_add_f32_e32 v207, v207, v103
	v_mov_b32_e32 v143, v207
	v_mov_b32_e32 v144, v207
	s_nop 1
	v_permlane16_swap_b32_e32 v143, v144
	v_add_f32_e32 v207, v143, v144
	v_mov_b32_e32 v143, v207
	v_mov_b32_e32 v144, v207
	s_nop 1
	v_permlane32_swap_b32_e32 v143, v144
	v_add_f32_e32 v207, v143, v144
	v_sub_f32_e32 v8, v8, v208
	v_sub_f32_e32 v9, v9, v208
	v_sub_f32_e32 v10, v10, v208
	v_sub_f32_e32 v11, v11, v208
	v_sub_f32_e32 v40, v40, v208
	v_sub_f32_e32 v41, v41, v208
	v_sub_f32_e32 v42, v42, v208
	v_sub_f32_e32 v43, v43, v208
	v_sub_f32_e32 v72, v72, v208
	v_sub_f32_e32 v73, v73, v208
	v_sub_f32_e32 v74, v74, v208
	v_sub_f32_e32 v75, v75, v208
	v_sub_f32_e32 v104, v104, v208
	v_sub_f32_e32 v105, v105, v208
	v_sub_f32_e32 v106, v106, v208
	v_sub_f32_e32 v107, v107, v208
	v_exp_f32_e32 v8, v8
	v_exp_f32_e32 v9, v9
	v_exp_f32_e32 v10, v10
	v_exp_f32_e32 v11, v11
	v_exp_f32_e32 v40, v40
	v_exp_f32_e32 v41, v41
	v_exp_f32_e32 v42, v42
	v_exp_f32_e32 v43, v43
	v_exp_f32_e32 v72, v72
	v_exp_f32_e32 v73, v73
	v_exp_f32_e32 v74, v74
	v_exp_f32_e32 v75, v75
	v_exp_f32_e32 v104, v104
	v_exp_f32_e32 v105, v105
	v_exp_f32_e32 v106, v106
	v_exp_f32_e32 v107, v107
	s_nop 0
	v_add_f32_e32 v208, v8, v9
	v_add_f32_e32 v208, v208, v10
	v_add_f32_e32 v208, v208, v11
	v_add_f32_e32 v208, v208, v40
	v_add_f32_e32 v208, v208, v41
	v_add_f32_e32 v208, v208, v42
	v_add_f32_e32 v208, v208, v43
	v_add_f32_e32 v208, v208, v72
	v_add_f32_e32 v208, v208, v73
	v_add_f32_e32 v208, v208, v74
	v_add_f32_e32 v208, v208, v75
	v_add_f32_e32 v208, v208, v104
	v_add_f32_e32 v208, v208, v105
	v_add_f32_e32 v208, v208, v106
	v_add_f32_e32 v208, v208, v107
	v_mov_b32_e32 v143, v208
	v_mov_b32_e32 v144, v208
	s_nop 1
	v_permlane16_swap_b32_e32 v143, v144
	v_add_f32_e32 v208, v143, v144
	v_mov_b32_e32 v143, v208
	v_mov_b32_e32 v144, v208
	s_nop 1
	v_permlane32_swap_b32_e32 v143, v144
	v_add_f32_e32 v208, v143, v144
	v_sub_f32_e32 v12, v12, v209
	v_sub_f32_e32 v13, v13, v209
	v_sub_f32_e32 v14, v14, v209
	v_sub_f32_e32 v15, v15, v209
	v_sub_f32_e32 v44, v44, v209
	v_sub_f32_e32 v45, v45, v209
	v_sub_f32_e32 v46, v46, v209
	v_sub_f32_e32 v47, v47, v209
	v_sub_f32_e32 v76, v76, v209
	v_sub_f32_e32 v77, v77, v209
	v_sub_f32_e32 v78, v78, v209
	v_sub_f32_e32 v79, v79, v209
	v_sub_f32_e32 v108, v108, v209
	v_sub_f32_e32 v109, v109, v209
	v_sub_f32_e32 v110, v110, v209
	v_sub_f32_e32 v111, v111, v209
	v_exp_f32_e32 v12, v12
	v_exp_f32_e32 v13, v13
	v_exp_f32_e32 v14, v14
	v_exp_f32_e32 v15, v15
	v_exp_f32_e32 v44, v44
	v_exp_f32_e32 v45, v45
	v_exp_f32_e32 v46, v46
	v_exp_f32_e32 v47, v47
	v_exp_f32_e32 v76, v76
	v_exp_f32_e32 v77, v77
	v_exp_f32_e32 v78, v78
	v_exp_f32_e32 v79, v79
	v_exp_f32_e32 v108, v108
	v_exp_f32_e32 v109, v109
	v_exp_f32_e32 v110, v110
	v_exp_f32_e32 v111, v111
	s_nop 0
	v_add_f32_e32 v209, v12, v13
	v_add_f32_e32 v209, v209, v14
	v_add_f32_e32 v209, v209, v15
	v_add_f32_e32 v209, v209, v44
	v_add_f32_e32 v209, v209, v45
	v_add_f32_e32 v209, v209, v46
	v_add_f32_e32 v209, v209, v47
	v_add_f32_e32 v209, v209, v76
	v_add_f32_e32 v209, v209, v77
	v_add_f32_e32 v209, v209, v78
	v_add_f32_e32 v209, v209, v79
	v_add_f32_e32 v209, v209, v108
	v_add_f32_e32 v209, v209, v109
	v_add_f32_e32 v209, v209, v110
	v_add_f32_e32 v209, v209, v111
	v_mov_b32_e32 v143, v209
	v_mov_b32_e32 v144, v209
	s_nop 1
	v_permlane16_swap_b32_e32 v143, v144
	v_add_f32_e32 v209, v143, v144
	v_mov_b32_e32 v143, v209
	v_mov_b32_e32 v144, v209
	s_nop 1
	v_permlane32_swap_b32_e32 v143, v144
	v_add_f32_e32 v209, v143, v144
	v_sub_f32_e32 v16, v16, v210
	v_sub_f32_e32 v17, v17, v210
	v_sub_f32_e32 v18, v18, v210
	v_sub_f32_e32 v19, v19, v210
	v_sub_f32_e32 v48, v48, v210
	v_sub_f32_e32 v49, v49, v210
	v_sub_f32_e32 v50, v50, v210
	v_sub_f32_e32 v51, v51, v210
	v_sub_f32_e32 v80, v80, v210
	v_sub_f32_e32 v81, v81, v210
	v_sub_f32_e32 v82, v82, v210
	v_sub_f32_e32 v83, v83, v210
	v_sub_f32_e32 v112, v112, v210
	v_sub_f32_e32 v113, v113, v210
	v_sub_f32_e32 v114, v114, v210
	v_sub_f32_e32 v115, v115, v210
	v_exp_f32_e32 v16, v16
	v_exp_f32_e32 v17, v17
	v_exp_f32_e32 v18, v18
	v_exp_f32_e32 v19, v19
	v_exp_f32_e32 v48, v48
	v_exp_f32_e32 v49, v49
	v_exp_f32_e32 v50, v50
	v_exp_f32_e32 v51, v51
	v_exp_f32_e32 v80, v80
	v_exp_f32_e32 v81, v81
	v_exp_f32_e32 v82, v82
	v_exp_f32_e32 v83, v83
	v_exp_f32_e32 v112, v112
	v_exp_f32_e32 v113, v113
	v_exp_f32_e32 v114, v114
	v_exp_f32_e32 v115, v115
	s_nop 0
	v_add_f32_e32 v210, v16, v17
	v_add_f32_e32 v210, v210, v18
	v_add_f32_e32 v210, v210, v19
	v_add_f32_e32 v210, v210, v48
	v_add_f32_e32 v210, v210, v49
	v_add_f32_e32 v210, v210, v50
	v_add_f32_e32 v210, v210, v51
	v_add_f32_e32 v210, v210, v80
	v_add_f32_e32 v210, v210, v81
	v_add_f32_e32 v210, v210, v82
	v_add_f32_e32 v210, v210, v83
	v_add_f32_e32 v210, v210, v112
	v_add_f32_e32 v210, v210, v113
	v_add_f32_e32 v210, v210, v114
	v_add_f32_e32 v210, v210, v115
	v_mov_b32_e32 v143, v210
	v_mov_b32_e32 v144, v210
	s_nop 1
	v_permlane16_swap_b32_e32 v143, v144
	v_add_f32_e32 v210, v143, v144
	v_mov_b32_e32 v143, v210
	v_mov_b32_e32 v144, v210
	s_nop 1
	v_permlane32_swap_b32_e32 v143, v144
	v_add_f32_e32 v210, v143, v144
	v_sub_f32_e32 v20, v20, v211
	v_sub_f32_e32 v21, v21, v211
	v_sub_f32_e32 v22, v22, v211
	v_sub_f32_e32 v23, v23, v211
	v_sub_f32_e32 v52, v52, v211
	v_sub_f32_e32 v53, v53, v211
	v_sub_f32_e32 v54, v54, v211
	v_sub_f32_e32 v55, v55, v211
	v_sub_f32_e32 v84, v84, v211
	v_sub_f32_e32 v85, v85, v211
	v_sub_f32_e32 v86, v86, v211
	v_sub_f32_e32 v87, v87, v211
	v_sub_f32_e32 v116, v116, v211
	v_sub_f32_e32 v117, v117, v211
	v_sub_f32_e32 v118, v118, v211
	v_sub_f32_e32 v119, v119, v211
	v_exp_f32_e32 v20, v20
	v_exp_f32_e32 v21, v21
	v_exp_f32_e32 v22, v22
	v_exp_f32_e32 v23, v23
	v_exp_f32_e32 v52, v52
	v_exp_f32_e32 v53, v53
	v_exp_f32_e32 v54, v54
	v_exp_f32_e32 v55, v55
	v_exp_f32_e32 v84, v84
	v_exp_f32_e32 v85, v85
	v_exp_f32_e32 v86, v86
	v_exp_f32_e32 v87, v87
	v_exp_f32_e32 v116, v116
	v_exp_f32_e32 v117, v117
	v_exp_f32_e32 v118, v118
	v_exp_f32_e32 v119, v119
	s_nop 0
	v_add_f32_e32 v211, v20, v21
	v_add_f32_e32 v211, v211, v22
	v_add_f32_e32 v211, v211, v23
	v_add_f32_e32 v211, v211, v52
	v_add_f32_e32 v211, v211, v53
	v_add_f32_e32 v211, v211, v54
	v_add_f32_e32 v211, v211, v55
	v_add_f32_e32 v211, v211, v84
	v_add_f32_e32 v211, v211, v85
	v_add_f32_e32 v211, v211, v86
	v_add_f32_e32 v211, v211, v87
	v_add_f32_e32 v211, v211, v116
	v_add_f32_e32 v211, v211, v117
	v_add_f32_e32 v211, v211, v118
	v_add_f32_e32 v211, v211, v119
	v_mov_b32_e32 v143, v211
	v_mov_b32_e32 v144, v211
	s_nop 1
	v_permlane16_swap_b32_e32 v143, v144
	v_add_f32_e32 v211, v143, v144
	v_mov_b32_e32 v143, v211
	v_mov_b32_e32 v144, v211
	s_nop 1
	v_permlane32_swap_b32_e32 v143, v144
	v_add_f32_e32 v211, v143, v144
	v_sub_f32_e32 v24, v24, v212
	v_sub_f32_e32 v25, v25, v212
	v_sub_f32_e32 v26, v26, v212
	v_sub_f32_e32 v27, v27, v212
	v_sub_f32_e32 v56, v56, v212
	v_sub_f32_e32 v57, v57, v212
	v_sub_f32_e32 v58, v58, v212
	v_sub_f32_e32 v59, v59, v212
	v_sub_f32_e32 v88, v88, v212
	v_sub_f32_e32 v89, v89, v212
	v_sub_f32_e32 v90, v90, v212
	v_sub_f32_e32 v91, v91, v212
	v_sub_f32_e32 v120, v120, v212
	v_sub_f32_e32 v121, v121, v212
	v_sub_f32_e32 v122, v122, v212
	v_sub_f32_e32 v123, v123, v212
	v_exp_f32_e32 v24, v24
	v_exp_f32_e32 v25, v25
	v_exp_f32_e32 v26, v26
	v_exp_f32_e32 v27, v27
	v_exp_f32_e32 v56, v56
	v_exp_f32_e32 v57, v57
	v_exp_f32_e32 v58, v58
	v_exp_f32_e32 v59, v59
	v_exp_f32_e32 v88, v88
	v_exp_f32_e32 v89, v89
	v_exp_f32_e32 v90, v90
	v_exp_f32_e32 v91, v91
	v_exp_f32_e32 v120, v120
	v_exp_f32_e32 v121, v121
	v_exp_f32_e32 v122, v122
	v_exp_f32_e32 v123, v123
	s_nop 0
	v_add_f32_e32 v212, v24, v25
	v_add_f32_e32 v212, v212, v26
	v_add_f32_e32 v212, v212, v27
	v_add_f32_e32 v212, v212, v56
	v_add_f32_e32 v212, v212, v57
	v_add_f32_e32 v212, v212, v58
	v_add_f32_e32 v212, v212, v59
	v_add_f32_e32 v212, v212, v88
	v_add_f32_e32 v212, v212, v89
	v_add_f32_e32 v212, v212, v90
	v_add_f32_e32 v212, v212, v91
	v_add_f32_e32 v212, v212, v120
	v_add_f32_e32 v212, v212, v121
	v_add_f32_e32 v212, v212, v122
	v_add_f32_e32 v212, v212, v123
	v_mov_b32_e32 v143, v212
	v_mov_b32_e32 v144, v212
	s_nop 1
	v_permlane16_swap_b32_e32 v143, v144
	v_add_f32_e32 v212, v143, v144
	v_mov_b32_e32 v143, v212
	v_mov_b32_e32 v144, v212
	s_nop 1
	v_permlane32_swap_b32_e32 v143, v144
	v_add_f32_e32 v212, v143, v144
	v_sub_f32_e32 v28, v28, v213
	v_sub_f32_e32 v29, v29, v213
	v_sub_f32_e32 v30, v30, v213
	v_sub_f32_e32 v31, v31, v213
	v_sub_f32_e32 v60, v60, v213
	v_sub_f32_e32 v61, v61, v213
	v_sub_f32_e32 v62, v62, v213
	v_sub_f32_e32 v63, v63, v213
	v_sub_f32_e32 v92, v92, v213
	v_sub_f32_e32 v93, v93, v213
	v_sub_f32_e32 v94, v94, v213
	v_sub_f32_e32 v95, v95, v213
	v_sub_f32_e32 v124, v124, v213
	v_sub_f32_e32 v125, v125, v213
	v_sub_f32_e32 v126, v126, v213
	v_sub_f32_e32 v127, v127, v213
	v_exp_f32_e32 v28, v28
	v_exp_f32_e32 v29, v29
	v_exp_f32_e32 v30, v30
	v_exp_f32_e32 v31, v31
	v_exp_f32_e32 v60, v60
	v_exp_f32_e32 v61, v61
	v_exp_f32_e32 v62, v62
	v_exp_f32_e32 v63, v63
	v_exp_f32_e32 v92, v92
	v_exp_f32_e32 v93, v93
	v_exp_f32_e32 v94, v94
	v_exp_f32_e32 v95, v95
	v_exp_f32_e32 v124, v124
	v_exp_f32_e32 v125, v125
	v_exp_f32_e32 v126, v126
	v_exp_f32_e32 v127, v127
	s_nop 0
	v_add_f32_e32 v213, v28, v29
	v_add_f32_e32 v213, v213, v30
	v_add_f32_e32 v213, v213, v31
	v_add_f32_e32 v213, v213, v60
	v_add_f32_e32 v213, v213, v61
	v_add_f32_e32 v213, v213, v62
	v_add_f32_e32 v213, v213, v63
	v_add_f32_e32 v213, v213, v92
	v_add_f32_e32 v213, v213, v93
	v_add_f32_e32 v213, v213, v94
	v_add_f32_e32 v213, v213, v95
	v_add_f32_e32 v213, v213, v124
	v_add_f32_e32 v213, v213, v125
	v_add_f32_e32 v213, v213, v126
	v_add_f32_e32 v213, v213, v127
	v_mov_b32_e32 v143, v213
	v_mov_b32_e32 v144, v213
	s_nop 1
	v_permlane16_swap_b32_e32 v143, v144
	v_add_f32_e32 v213, v143, v144
	v_mov_b32_e32 v143, v213
	v_mov_b32_e32 v144, v213
	s_nop 1
	v_permlane32_swap_b32_e32 v143, v144
	v_add_f32_e32 v213, v143, v144
	s_and_saveexec_b64 s[72:73], s[46:47]
	ds_write_b32 v142, v206
	ds_write_b32 v142, v207 offset:256
	ds_write_b32 v142, v208 offset:512
	ds_write_b32 v142, v209 offset:768
	ds_write_b32 v142, v210 offset:1024
	ds_write_b32 v142, v211 offset:1280
	ds_write_b32 v142, v212 offset:1536
	ds_write_b32 v142, v213 offset:1792
	s_or_b64 exec, exec, s[72:73]
	s_waitcnt lgkmcnt(0)
	s_barrier
	ds_read_b128 v[214:217], v141
	ds_read_b128 v[218:221], v141 offset:256
	ds_read_b128 v[222:225], v141 offset:512
	ds_read_b128 v[226:229], v141 offset:768
	ds_read_b128 v[236:239], v141 offset:1024
	ds_read_b128 v[240:243], v141 offset:1280
	ds_read_b128 v[248:251], v141 offset:1536
	ds_read_b128 v[146:149], v141 offset:1792
	s_waitcnt lgkmcnt(7)
	v_add_f32_e32 v214, v214, v215
	v_add_f32_e32 v216, v216, v217
	v_add_f32_e32 v214, v214, v216
	v_rcp_f32_e32 v206, v214
	s_waitcnt lgkmcnt(6)
	v_add_f32_e32 v218, v218, v219
	v_add_f32_e32 v220, v220, v221
	v_add_f32_e32 v218, v218, v220
	v_rcp_f32_e32 v207, v218
	s_waitcnt lgkmcnt(5)
	v_add_f32_e32 v222, v222, v223
	v_add_f32_e32 v224, v224, v225
	v_add_f32_e32 v222, v222, v224
	v_rcp_f32_e32 v208, v222
	s_waitcnt lgkmcnt(4)
	v_add_f32_e32 v226, v226, v227
	v_add_f32_e32 v228, v228, v229
	v_add_f32_e32 v226, v226, v228
	v_rcp_f32_e32 v209, v226
	s_waitcnt lgkmcnt(3)
	v_add_f32_e32 v236, v236, v237
	v_add_f32_e32 v238, v238, v239
	v_add_f32_e32 v236, v236, v238
	v_rcp_f32_e32 v210, v236
	s_waitcnt lgkmcnt(2)
	v_add_f32_e32 v240, v240, v241
	v_add_f32_e32 v242, v242, v243
	v_add_f32_e32 v240, v240, v242
	v_rcp_f32_e32 v211, v240
	s_waitcnt lgkmcnt(1)
	v_add_f32_e32 v248, v248, v249
	v_add_f32_e32 v250, v250, v251
	v_add_f32_e32 v248, v248, v250
	v_rcp_f32_e32 v212, v248
	s_waitcnt lgkmcnt(0)
	v_add_f32_e32 v146, v146, v147
	v_add_f32_e32 v148, v148, v149
	v_add_f32_e32 v146, v146, v148
	v_rcp_f32_e32 v213, v146
	v_and_b32_e32 v143, 7, v133
	v_lshrrev_b32_e32 v144, 1, v134
	v_and_b32_e32 v145, 1, v134
	v_lshlrev_b32_e32 v138, 7, v133
	v_lshl_add_u32 v138, v135, 13, v138
	v_add_u32_e32 v138, 0x10010, v138
	v_lshl_add_u32 v138, v145, 3, v138
	v_or_b32_e32 v145, 0, v144
	v_xor_b32_e32 v145, v145, v143
	v_lshl_add_u32 v180, v145, 4, v138
	v_or_b32_e32 v145, 2, v144
	v_xor_b32_e32 v145, v145, v143
	v_lshl_add_u32 v181, v145, 4, v138
	v_or_b32_e32 v145, 4, v144
	v_xor_b32_e32 v145, v145, v143
	v_lshl_add_u32 v182, v145, 4, v138
	v_or_b32_e32 v145, 6, v144
	v_xor_b32_e32 v145, v145, v143
	v_lshl_add_u32 v183, v145, 4, v138
	v_and_b32_e32 v143, 63, v150
	v_lshrrev_b32_e32 v144, 3, v143
	v_and_b32_e32 v145, 7, v143
	v_xor_b32_e32 v202, v144, v145
	v_lshlrev_b32_e32 v202, 4, v202
	v_lshl_add_u32 v202, v144, 7, v202
	v_lshl_add_u32 v202, v135, 13, v202
	v_add_u32_e32 v202, 0x10010, v202
	v_lshl_add_u32 v143, v136, 7, v144
	v_add_u32_e32 v204, s19, v143
	v_ashrrev_i32_e32 v205, 31, v204
	v_lshlrev_b64 v[204:205], 11, v[204:205]
	v_lshlrev_b32_e32 v143, 6, v137
	v_or_b32_e32 v143, s20, v143
	v_lshlrev_b32_e32 v143, 1, v143
	v_lshl_add_u32 v138, v145, 4, v143
	v_mov_b32_e32 v139, 0
	v_lshl_add_u64 v[204:205], s[10:11], 0, v[204:205]
	v_lshl_add_u64 v[204:205], v[204:205], 0, v[138:139]
	s_mov_b64 s[72:73], 0x4000
	v_mul_f32_e32 v0, v0, v206
	v_mul_f32_e32 v1, v1, v206
	v_mul_f32_e32 v2, v2, v206
	v_mul_f32_e32 v3, v3, v206
	v_cvt_pk_bf16_f32 v0, v0, v1
	v_cvt_pk_bf16_f32 v1, v2, v3
	ds_write_b64 v180, v[0:1]
	v_mul_f32_e32 v32, v32, v206
	v_mul_f32_e32 v33, v33, v206
	v_mul_f32_e32 v34, v34, v206
	v_mul_f32_e32 v35, v35, v206
	v_cvt_pk_bf16_f32 v32, v32, v33
	v_cvt_pk_bf16_f32 v33, v34, v35
	ds_write_b64 v181, v[32:33]
	v_mul_f32_e32 v64, v64, v206
	v_mul_f32_e32 v65, v65, v206
	v_mul_f32_e32 v66, v66, v206
	v_mul_f32_e32 v67, v67, v206
	v_cvt_pk_bf16_f32 v64, v64, v65
	v_cvt_pk_bf16_f32 v65, v66, v67
	ds_write_b64 v182, v[64:65]
	v_mul_f32_e32 v96, v96, v206
	v_mul_f32_e32 v97, v97, v206
	v_mul_f32_e32 v98, v98, v206
	v_mul_f32_e32 v99, v99, v206
	v_cvt_pk_bf16_f32 v96, v96, v97
	v_cvt_pk_bf16_f32 v97, v98, v99
	ds_write_b64 v183, v[96:97]
	v_mul_f32_e32 v4, v4, v207
	v_mul_f32_e32 v5, v5, v207
	v_mul_f32_e32 v6, v6, v207
	v_mul_f32_e32 v7, v7, v207
	v_cvt_pk_bf16_f32 v4, v4, v5
	v_cvt_pk_bf16_f32 v5, v6, v7
	ds_write_b64 v180, v[4:5] offset:2048
	v_mul_f32_e32 v36, v36, v207
	v_mul_f32_e32 v37, v37, v207
	v_mul_f32_e32 v38, v38, v207
	v_mul_f32_e32 v39, v39, v207
	v_cvt_pk_bf16_f32 v36, v36, v37
	v_cvt_pk_bf16_f32 v37, v38, v39
	ds_write_b64 v181, v[36:37] offset:2048
	v_mul_f32_e32 v68, v68, v207
	v_mul_f32_e32 v69, v69, v207
	v_mul_f32_e32 v70, v70, v207
	v_mul_f32_e32 v71, v71, v207
	v_cvt_pk_bf16_f32 v68, v68, v69
	v_cvt_pk_bf16_f32 v69, v70, v71
	ds_write_b64 v182, v[68:69] offset:2048
	v_mul_f32_e32 v100, v100, v207
	v_mul_f32_e32 v101, v101, v207
	v_mul_f32_e32 v102, v102, v207
	v_mul_f32_e32 v103, v103, v207
	v_cvt_pk_bf16_f32 v100, v100, v101
	v_cvt_pk_bf16_f32 v101, v102, v103
	ds_write_b64 v183, v[100:101] offset:2048
	v_mul_f32_e32 v8, v8, v208
	v_mul_f32_e32 v9, v9, v208
	v_mul_f32_e32 v10, v10, v208
	v_mul_f32_e32 v11, v11, v208
	v_cvt_pk_bf16_f32 v8, v8, v9
	v_cvt_pk_bf16_f32 v9, v10, v11
	ds_write_b64 v180, v[8:9] offset:4096
	v_mul_f32_e32 v40, v40, v208
	v_mul_f32_e32 v41, v41, v208
	v_mul_f32_e32 v42, v42, v208
	v_mul_f32_e32 v43, v43, v208
	v_cvt_pk_bf16_f32 v40, v40, v41
	v_cvt_pk_bf16_f32 v41, v42, v43
	ds_write_b64 v181, v[40:41] offset:4096
	v_mul_f32_e32 v72, v72, v208
	v_mul_f32_e32 v73, v73, v208
	v_mul_f32_e32 v74, v74, v208
	v_mul_f32_e32 v75, v75, v208
	v_cvt_pk_bf16_f32 v72, v72, v73
	v_cvt_pk_bf16_f32 v73, v74, v75
	ds_write_b64 v182, v[72:73] offset:4096
	v_mul_f32_e32 v104, v104, v208
	v_mul_f32_e32 v105, v105, v208
	v_mul_f32_e32 v106, v106, v208
	v_mul_f32_e32 v107, v107, v208
	v_cvt_pk_bf16_f32 v104, v104, v105
	v_cvt_pk_bf16_f32 v105, v106, v107
	ds_write_b64 v183, v[104:105] offset:4096
	v_mul_f32_e32 v12, v12, v209
	v_mul_f32_e32 v13, v13, v209
	v_mul_f32_e32 v14, v14, v209
	v_mul_f32_e32 v15, v15, v209
	v_cvt_pk_bf16_f32 v12, v12, v13
	v_cvt_pk_bf16_f32 v13, v14, v15
	ds_write_b64 v180, v[12:13] offset:6144
	v_mul_f32_e32 v44, v44, v209
	v_mul_f32_e32 v45, v45, v209
	v_mul_f32_e32 v46, v46, v209
	v_mul_f32_e32 v47, v47, v209
	v_cvt_pk_bf16_f32 v44, v44, v45
	v_cvt_pk_bf16_f32 v45, v46, v47
	ds_write_b64 v181, v[44:45] offset:6144
	v_mul_f32_e32 v76, v76, v209
	v_mul_f32_e32 v77, v77, v209
	v_mul_f32_e32 v78, v78, v209
	v_mul_f32_e32 v79, v79, v209
	v_cvt_pk_bf16_f32 v76, v76, v77
	v_cvt_pk_bf16_f32 v77, v78, v79
	ds_write_b64 v182, v[76:77] offset:6144
	v_mul_f32_e32 v108, v108, v209
	v_mul_f32_e32 v109, v109, v209
	v_mul_f32_e32 v110, v110, v209
	v_mul_f32_e32 v111, v111, v209
	v_cvt_pk_bf16_f32 v108, v108, v109
	v_cvt_pk_bf16_f32 v109, v110, v111
	ds_write_b64 v183, v[108:109] offset:6144
	s_waitcnt lgkmcnt(0)
	ds_read_b128 v[0:3], v202
	ds_read_b128 v[4:7], v202 offset:1024
	ds_read_b128 v[8:11], v202 offset:2048
	ds_read_b128 v[12:15], v202 offset:3072
	ds_read_b128 v[32:35], v202 offset:4096
	ds_read_b128 v[36:39], v202 offset:5120
	ds_read_b128 v[40:43], v202 offset:6144
	ds_read_b128 v[44:47], v202 offset:7168
	s_waitcnt lgkmcnt(7)
	global_store_dwordx4 v[204:205], v[0:3], off
	v_lshl_add_u64 v[204:205], v[204:205], 0, s[72:73]
	s_waitcnt lgkmcnt(6)
	global_store_dwordx4 v[204:205], v[4:7], off
	v_lshl_add_u64 v[204:205], v[204:205], 0, s[72:73]
	s_waitcnt lgkmcnt(5)
	global_store_dwordx4 v[204:205], v[8:11], off
	v_lshl_add_u64 v[204:205], v[204:205], 0, s[72:73]
	s_waitcnt lgkmcnt(4)
	global_store_dwordx4 v[204:205], v[12:15], off
	v_lshl_add_u64 v[204:205], v[204:205], 0, s[72:73]
	s_waitcnt lgkmcnt(3)
	global_store_dwordx4 v[204:205], v[32:35], off
	v_lshl_add_u64 v[204:205], v[204:205], 0, s[72:73]
	s_waitcnt lgkmcnt(2)
	global_store_dwordx4 v[204:205], v[36:39], off
	v_lshl_add_u64 v[204:205], v[204:205], 0, s[72:73]
	s_waitcnt lgkmcnt(1)
	global_store_dwordx4 v[204:205], v[40:43], off
	v_lshl_add_u64 v[204:205], v[204:205], 0, s[72:73]
	s_waitcnt lgkmcnt(0)
	global_store_dwordx4 v[204:205], v[44:47], off
	v_lshl_add_u64 v[204:205], v[204:205], 0, s[72:73]
	v_mul_f32_e32 v16, v16, v210
	v_mul_f32_e32 v17, v17, v210
	v_mul_f32_e32 v18, v18, v210
	v_mul_f32_e32 v19, v19, v210
	v_cvt_pk_bf16_f32 v16, v16, v17
	v_cvt_pk_bf16_f32 v17, v18, v19
	ds_write_b64 v180, v[16:17]
	v_mul_f32_e32 v48, v48, v210
	v_mul_f32_e32 v49, v49, v210
	v_mul_f32_e32 v50, v50, v210
	v_mul_f32_e32 v51, v51, v210
	v_cvt_pk_bf16_f32 v48, v48, v49
	v_cvt_pk_bf16_f32 v49, v50, v51
	ds_write_b64 v181, v[48:49]
	v_mul_f32_e32 v80, v80, v210
	v_mul_f32_e32 v81, v81, v210
	v_mul_f32_e32 v82, v82, v210
	v_mul_f32_e32 v83, v83, v210
	v_cvt_pk_bf16_f32 v80, v80, v81
	v_cvt_pk_bf16_f32 v81, v82, v83
	ds_write_b64 v182, v[80:81]
	v_mul_f32_e32 v112, v112, v210
	v_mul_f32_e32 v113, v113, v210
	v_mul_f32_e32 v114, v114, v210
	v_mul_f32_e32 v115, v115, v210
	v_cvt_pk_bf16_f32 v112, v112, v113
	v_cvt_pk_bf16_f32 v113, v114, v115
	ds_write_b64 v183, v[112:113]
	v_mul_f32_e32 v20, v20, v211
	v_mul_f32_e32 v21, v21, v211
	v_mul_f32_e32 v22, v22, v211
	v_mul_f32_e32 v23, v23, v211
	v_cvt_pk_bf16_f32 v20, v20, v21
	v_cvt_pk_bf16_f32 v21, v22, v23
	ds_write_b64 v180, v[20:21] offset:2048
	v_mul_f32_e32 v52, v52, v211
	v_mul_f32_e32 v53, v53, v211
	v_mul_f32_e32 v54, v54, v211
	v_mul_f32_e32 v55, v55, v211
	v_cvt_pk_bf16_f32 v52, v52, v53
	v_cvt_pk_bf16_f32 v53, v54, v55
	ds_write_b64 v181, v[52:53] offset:2048
	v_mul_f32_e32 v84, v84, v211
	v_mul_f32_e32 v85, v85, v211
	v_mul_f32_e32 v86, v86, v211
	v_mul_f32_e32 v87, v87, v211
	v_cvt_pk_bf16_f32 v84, v84, v85
	v_cvt_pk_bf16_f32 v85, v86, v87
	ds_write_b64 v182, v[84:85] offset:2048
	v_mul_f32_e32 v116, v116, v211
	v_mul_f32_e32 v117, v117, v211
	v_mul_f32_e32 v118, v118, v211
	v_mul_f32_e32 v119, v119, v211
	v_cvt_pk_bf16_f32 v116, v116, v117
	v_cvt_pk_bf16_f32 v117, v118, v119
	ds_write_b64 v183, v[116:117] offset:2048
	v_mul_f32_e32 v24, v24, v212
	v_mul_f32_e32 v25, v25, v212
	v_mul_f32_e32 v26, v26, v212
	v_mul_f32_e32 v27, v27, v212
	v_cvt_pk_bf16_f32 v24, v24, v25
	v_cvt_pk_bf16_f32 v25, v26, v27
	ds_write_b64 v180, v[24:25] offset:4096
	v_mul_f32_e32 v56, v56, v212
	v_mul_f32_e32 v57, v57, v212
	v_mul_f32_e32 v58, v58, v212
	v_mul_f32_e32 v59, v59, v212
	v_cvt_pk_bf16_f32 v56, v56, v57
	v_cvt_pk_bf16_f32 v57, v58, v59
	ds_write_b64 v181, v[56:57] offset:4096
	v_mul_f32_e32 v88, v88, v212
	v_mul_f32_e32 v89, v89, v212
	v_mul_f32_e32 v90, v90, v212
	v_mul_f32_e32 v91, v91, v212
	v_cvt_pk_bf16_f32 v88, v88, v89
	v_cvt_pk_bf16_f32 v89, v90, v91
	ds_write_b64 v182, v[88:89] offset:4096
	v_mul_f32_e32 v120, v120, v212
	v_mul_f32_e32 v121, v121, v212
	v_mul_f32_e32 v122, v122, v212
	v_mul_f32_e32 v123, v123, v212
	v_cvt_pk_bf16_f32 v120, v120, v121
	v_cvt_pk_bf16_f32 v121, v122, v123
	ds_write_b64 v183, v[120:121] offset:4096
	v_mul_f32_e32 v28, v28, v213
	v_mul_f32_e32 v29, v29, v213
	v_mul_f32_e32 v30, v30, v213
	v_mul_f32_e32 v31, v31, v213
	v_cvt_pk_bf16_f32 v28, v28, v29
	v_cvt_pk_bf16_f32 v29, v30, v31
	ds_write_b64 v180, v[28:29] offset:6144
	v_mul_f32_e32 v60, v60, v213
	v_mul_f32_e32 v61, v61, v213
	v_mul_f32_e32 v62, v62, v213
	v_mul_f32_e32 v63, v63, v213
	v_cvt_pk_bf16_f32 v60, v60, v61
	v_cvt_pk_bf16_f32 v61, v62, v63
	ds_write_b64 v181, v[60:61] offset:6144
	v_mul_f32_e32 v92, v92, v213
	v_mul_f32_e32 v93, v93, v213
	v_mul_f32_e32 v94, v94, v213
	v_mul_f32_e32 v95, v95, v213
	v_cvt_pk_bf16_f32 v92, v92, v93
	v_cvt_pk_bf16_f32 v93, v94, v95
	ds_write_b64 v182, v[92:93] offset:6144
	v_mul_f32_e32 v124, v124, v213
	v_mul_f32_e32 v125, v125, v213
	v_mul_f32_e32 v126, v126, v213
	v_mul_f32_e32 v127, v127, v213
	v_cvt_pk_bf16_f32 v124, v124, v125
	v_cvt_pk_bf16_f32 v125, v126, v127
	ds_write_b64 v183, v[124:125] offset:6144
	s_waitcnt lgkmcnt(0)
	ds_read_b128 v[16:19], v202
	ds_read_b128 v[20:23], v202 offset:1024
	ds_read_b128 v[24:27], v202 offset:2048
	ds_read_b128 v[28:31], v202 offset:3072
	ds_read_b128 v[48:51], v202 offset:4096
	ds_read_b128 v[52:55], v202 offset:5120
	ds_read_b128 v[56:59], v202 offset:6144
	ds_read_b128 v[60:63], v202 offset:7168
	s_waitcnt lgkmcnt(7)
	global_store_dwordx4 v[204:205], v[16:19], off
	v_lshl_add_u64 v[204:205], v[204:205], 0, s[72:73]
	s_waitcnt lgkmcnt(6)
	global_store_dwordx4 v[204:205], v[20:23], off
	v_lshl_add_u64 v[204:205], v[204:205], 0, s[72:73]
	s_waitcnt lgkmcnt(5)
	global_store_dwordx4 v[204:205], v[24:27], off
	v_lshl_add_u64 v[204:205], v[204:205], 0, s[72:73]
	s_waitcnt lgkmcnt(4)
	global_store_dwordx4 v[204:205], v[28:31], off
	v_lshl_add_u64 v[204:205], v[204:205], 0, s[72:73]
	s_waitcnt lgkmcnt(3)
	global_store_dwordx4 v[204:205], v[48:51], off
	v_lshl_add_u64 v[204:205], v[204:205], 0, s[72:73]
	s_waitcnt lgkmcnt(2)
	global_store_dwordx4 v[204:205], v[52:55], off
	v_lshl_add_u64 v[204:205], v[204:205], 0, s[72:73]
	s_waitcnt lgkmcnt(1)
	global_store_dwordx4 v[204:205], v[56:59], off
	v_lshl_add_u64 v[204:205], v[204:205], 0, s[72:73]
	s_waitcnt lgkmcnt(0)
	global_store_dwordx4 v[204:205], v[60:63], off
	v_lshl_add_u64 v[204:205], v[204:205], 0, s[72:73]
	s_and_b64 vcc, exec, s[16:17]
	s_branch .Lst5_fin
